# attention PV: only the first group's 8 V fragment reads before the first wait; second group's reads behind the first MFMA
# baseline (speedup 1.0000x reference)
; #define SBAR() __builtin_amdgcn_sched_barrier(0)
; #define VF_WAIT(N) do { asm volatile("s_waitcnt lgkmcnt(" #N ")" ::: "memory"); SBAR(); } while (0)
; #define DMA_V(t, sl) do { const char* b_ = Vb + (size_t)(t) * TSTRIDE; const unsigned d_ = RFL(vdst + (sl) * 32768); glds16(b_ + voff[0], d_); glds16(b_ + voff[1], d_ + 1024); glds16(b_ + voff[2], d_ + 2048); glds16(b_ + voff[3], d_ + 3072); } while (0)
; __device__ __forceinline__ void pv8(f32x16* o, int vb, bf16x8 pa0, bf16x8 pa1, bf16x8 pa2, bf16x8 pa3) {
;   VFrag fa, fb; const int vb2 = vb + 16384;
;   vf_read<0>(fa, vb);
;   vf_read<1>(fb, vb);  VF_WAIT(8); vf_mma(o[0], fa, pa0, pa1, pa2, pa3); SBAR();
;   vf_read<2>(fa, vb);  VF_WAIT(8); vf_mma(o[1], fb, pa0, pa1, pa2, pa3); SBAR();
;   vf_read<3>(fb, vb);  VF_WAIT(8); vf_mma(o[2], fa, pa0, pa1, pa2, pa3); SBAR();
; template <int mode> ...
;     ...
;     if (more) DMA_V(j + 2, s2);
.LBB0_363:
	v_lshl_add_u32 v220, s11, 15, v223
	ds_read_b64_tr_b16 v[144:145], v220 offset:0
	ds_read_b64_tr_b16 v[146:147], v220 offset:0x800
	ds_read_b64_tr_b16 v[148:149], v220 offset:0x1000
	ds_read_b64_tr_b16 v[150:151], v220 offset:0x1800
	ds_read_b64_tr_b16 v[152:153], v220 offset:0x2000
	ds_read_b64_tr_b16 v[154:155], v220 offset:0x2800
	ds_read_b64_tr_b16 v[156:157], v220 offset:0x3000
	ds_read_b64_tr_b16 v[158:159], v220 offset:0x3800
	s_waitcnt lgkmcnt(0)
	v_add_u32_e32 v221, 0x4000, v220
	v_mfma_f32_32x32x16_bf16 v[112:127], v[128:131], v[144:147], v[112:127]
	ds_read_b64_tr_b16 v[194:195], v220 offset:0x200
	ds_read_b64_tr_b16 v[196:197], v220 offset:0xa00
	ds_read_b64_tr_b16 v[214:215], v220 offset:0x1200
	ds_read_b64_tr_b16 v[216:217], v220 offset:0x1a00
	ds_read_b64_tr_b16 v[228:229], v220 offset:0x2200
	ds_read_b64_tr_b16 v[230:231], v220 offset:0x2a00
	ds_read_b64_tr_b16 v[232:233], v220 offset:0x3200
	ds_read_b64_tr_b16 v[234:235], v220 offset:0x3a00
	v_mfma_f32_32x32x16_bf16 v[112:127], v[132:135], v[148:151], v[112:127]
	v_mfma_f32_32x32x16_bf16 v[112:127], v[136:139], v[152:155], v[112:127]
	v_mfma_f32_32x32x16_bf16 v[112:127], v[140:143], v[156:159], v[112:127]
	ds_read_b64_tr_b16 v[144:145], v220 offset:0x400
	ds_read_b64_tr_b16 v[146:147], v220 offset:0xc00
	ds_read_b64_tr_b16 v[148:149], v220 offset:0x1400
	ds_read_b64_tr_b16 v[150:151], v220 offset:0x1c00
	ds_read_b64_tr_b16 v[152:153], v220 offset:0x2400
	ds_read_b64_tr_b16 v[154:155], v220 offset:0x2c00
	ds_read_b64_tr_b16 v[156:157], v220 offset:0x3400
	ds_read_b64_tr_b16 v[158:159], v220 offset:0x3c00
	s_waitcnt lgkmcnt(8)
	v_mfma_f32_32x32x16_bf16 v[96:111], v[128:131], v[194:197], v[96:111]
	v_mfma_f32_32x32x16_bf16 v[96:111], v[132:135], v[214:217], v[96:111]
	v_mfma_f32_32x32x16_bf16 v[96:111], v[136:139], v[228:231], v[96:111]
	v_mfma_f32_32x32x16_bf16 v[96:111], v[140:143], v[232:235], v[96:111]
	ds_read_b64_tr_b16 v[194:195], v220 offset:0x600
	ds_read_b64_tr_b16 v[196:197], v220 offset:0xe00
	ds_read_b64_tr_b16 v[214:215], v220 offset:0x1600
	ds_read_b64_tr_b16 v[216:217], v220 offset:0x1e00
	ds_read_b64_tr_b16 v[228:229], v220 offset:0x2600
	ds_read_b64_tr_b16 v[230:231], v220 offset:0x2e00
	ds_read_b64_tr_b16 v[232:233], v220 offset:0x3600
	ds_read_b64_tr_b16 v[234:235], v220 offset:0x3e00
	s_cbranch_vccnz .Lp0_nodma
	s_lshl_b32 s12, s9, 15
	s_add_i32 s12, s12, s7
	s_mov_b32 s13, m0
	s_mov_b32 m0, s12
	s_nop 0
	global_load_lds_dwordx4 v204, s[38:39]
	s_add_i32 s24, s12, 0x400
	s_mov_b32 m0, s24
	s_nop 0
	global_load_lds_dwordx4 v206, s[38:39]
	s_add_i32 s24, s12, 0x800
	s_mov_b32 m0, s24
	s_nop 0
	global_load_lds_dwordx4 v208, s[38:39]
	s_add_i32 s24, s12, 0xc00
	s_mov_b32 m0, s24
	s_nop 0
	global_load_lds_dwordx4 v210, s[38:39]
	s_mov_b32 m0, s13

; #define SBAR() __builtin_amdgcn_sched_barrier(0)
; #define VF_WAIT(N) do { asm volatile("s_waitcnt lgkmcnt(" #N ")" ::: "memory"); SBAR(); } while (0)
; #define DMA_V(t, sl) do { const char* b_ = Vb + (size_t)(t) * TSTRIDE; const unsigned d_ = RFL(vdst + (sl) * 32768); glds16(b_ + voff[0], d_); glds16(b_ + voff[1], d_ + 1024); glds16(b_ + voff[2], d_ + 2048); glds16(b_ + voff[3], d_ + 3072); } while (0)
; __device__ __forceinline__ void pv8(f32x16* o, int vb, bf16x8 pa0, bf16x8 pa1, bf16x8 pa2, bf16x8 pa3) {
;   VFrag fa, fb; const int vb2 = vb + 16384;
;   vf_read<0>(fa, vb);
;   vf_read<1>(fb, vb);  VF_WAIT(8); vf_mma(o[0], fa, pa0, pa1, pa2, pa3); SBAR();
;   vf_read<2>(fa, vb);  VF_WAIT(8); vf_mma(o[1], fb, pa0, pa1, pa2, pa3); SBAR();
;   vf_read<3>(fb, vb);  VF_WAIT(8); vf_mma(o[2], fa, pa0, pa1, pa2, pa3); SBAR();
; template <int mode> ...
;     ...
;     if (more) DMA_V(j + 2, s2);
.LBB0_396:
	v_lshl_add_u32 v231, s10, 15, v226
	ds_read_b64_tr_b16 v[144:145], v231 offset:0
	ds_read_b64_tr_b16 v[146:147], v231 offset:0x800
	ds_read_b64_tr_b16 v[148:149], v231 offset:0x1000
	ds_read_b64_tr_b16 v[150:151], v231 offset:0x1800
	ds_read_b64_tr_b16 v[152:153], v231 offset:0x2000
	ds_read_b64_tr_b16 v[154:155], v231 offset:0x2800
	ds_read_b64_tr_b16 v[156:157], v231 offset:0x3000
	ds_read_b64_tr_b16 v[158:159], v231 offset:0x3800
	s_waitcnt lgkmcnt(0)
	v_add_u32_e32 v236, 0x4000, v231
	v_mfma_f32_32x32x16_bf16 v[16:31], v[128:131], v[144:147], v[16:31]
	ds_read_b64_tr_b16 v[194:195], v231 offset:0x200
	ds_read_b64_tr_b16 v[196:197], v231 offset:0xa00
	ds_read_b64_tr_b16 v[214:215], v231 offset:0x1200
	ds_read_b64_tr_b16 v[216:217], v231 offset:0x1a00
	ds_read_b64_tr_b16 v[220:221], v231 offset:0x2200
	ds_read_b64_tr_b16 v[222:223], v231 offset:0x2a00
	ds_read_b64_tr_b16 v[232:233], v231 offset:0x3200
	ds_read_b64_tr_b16 v[234:235], v231 offset:0x3a00
	v_mfma_f32_32x32x16_bf16 v[16:31], v[132:135], v[148:151], v[16:31]
	v_mfma_f32_32x32x16_bf16 v[16:31], v[136:139], v[152:155], v[16:31]
	v_mfma_f32_32x32x16_bf16 v[16:31], v[140:143], v[156:159], v[16:31]
	ds_read_b64_tr_b16 v[144:145], v231 offset:0x400
	ds_read_b64_tr_b16 v[146:147], v231 offset:0xc00
	ds_read_b64_tr_b16 v[148:149], v231 offset:0x1400
	ds_read_b64_tr_b16 v[150:151], v231 offset:0x1c00
	ds_read_b64_tr_b16 v[152:153], v231 offset:0x2400
	ds_read_b64_tr_b16 v[154:155], v231 offset:0x2c00
	ds_read_b64_tr_b16 v[156:157], v231 offset:0x3400
	ds_read_b64_tr_b16 v[158:159], v231 offset:0x3c00
	s_waitcnt lgkmcnt(8)
	v_mfma_f32_32x32x16_bf16 v[32:47], v[128:131], v[194:197], v[32:47]
	v_mfma_f32_32x32x16_bf16 v[32:47], v[132:135], v[214:217], v[32:47]
	v_mfma_f32_32x32x16_bf16 v[32:47], v[136:139], v[220:223], v[32:47]
	v_mfma_f32_32x32x16_bf16 v[32:47], v[140:143], v[232:235], v[32:47]
	ds_read_b64_tr_b16 v[194:195], v231 offset:0x600
	ds_read_b64_tr_b16 v[196:197], v231 offset:0xe00
	ds_read_b64_tr_b16 v[214:215], v231 offset:0x1600
	ds_read_b64_tr_b16 v[216:217], v231 offset:0x1e00
	ds_read_b64_tr_b16 v[220:221], v231 offset:0x2600
	ds_read_b64_tr_b16 v[222:223], v231 offset:0x2e00
	ds_read_b64_tr_b16 v[232:233], v231 offset:0x3600
	ds_read_b64_tr_b16 v[234:235], v231 offset:0x3e00
	s_cbranch_vccnz .Lp1_nodma
	s_lshl_b32 s11, s7, 15
	s_add_i32 s11, s11, s5
	s_mov_b32 s12, m0
	s_mov_b32 m0, s11
	s_nop 0
	global_load_lds_dwordx4 v204, s[60:61]
	s_add_i32 s13, s11, 0x400
	s_mov_b32 m0, s13
	s_nop 0
	global_load_lds_dwordx4 v206, s[60:61]
	s_add_i32 s13, s11, 0x800
	s_mov_b32 m0, s13
	s_nop 0
	global_load_lds_dwordx4 v208, s[60:61]
	s_add_i32 s13, s11, 0xc00
	s_mov_b32 m0, s13
	s_nop 0
	global_load_lds_dwordx4 v210, s[60:61]
	s_mov_b32 m0, s12
